# full stack plus phase-0 section order swapped for workgroups 256..511 (rows pass before the weight transposes)
# speedup vs baseline: 1.0235x; 1.0012x over previous
.Lp0_ns2:
.LBB0_13:
	s_or_b64 exec, exec, s[0:1]
	s_mov_b32 s99, 0
	s_bitcmp1_b32 s96, 8
	s_cbranch_scc0 .Lp0_even
	s_lshl_b32 s48, s96, 2
	s_branch .LBB0_56
.Lp0_even:
	s_cmpk_lt_i32 s96, 0x600
	s_cbranch_scc1 .LBB0_15
	s_lshl_b32 s48, s96, 2
	s_cbranch_execz .LBB0_16
	s_branch .LBB0_56

.LBB0_56:
	s_cmp_eq_u32 s99, 1
	s_cbranch_scc1 .Lp0_back
	v_readlane_b32 s8, v237, 19
	v_readlane_b32 s9, v237, 20
	s_movk_i32 s4, 0x3820
	v_or_b32_e32 v1, 0x100, v0
	v_mov_b64_e32 v[26:27], s[8:9]
	v_mad_u64_u32 v[22:23], s[0:1], v0, s4, v[26:27]
	s_movk_i32 s5, 0x3000
	v_mad_u64_u32 v[2:3], s[0:1], v1, s4, v[26:27]
	s_mov_b64 s[2:3], 0x3800
	v_add_co_u32_e64 v12, s[0:1], s5, v2
	v_or_b32_e32 v1, 0x200, v0
	v_lshl_add_u64 v[10:11], v[2:3], 0, s[2:3]
	v_addc_co_u32_e64 v13, s[0:1], 0, v3, s[0:1]
	v_mad_u64_u32 v[14:15], s[0:1], v1, s4, v[26:27]
	s_barrier
	v_readlane_b32 s10, v237, 21
	v_readlane_b32 s11, v237, 22
	v_readlane_b32 s12, v237, 23
	v_readlane_b32 s13, v237, 24
	v_readlane_b32 s14, v237, 25
	v_readlane_b32 s15, v237, 26
	v_readlane_b32 s16, v237, 27
	v_readlane_b32 s17, v237, 28
	v_readlane_b32 s18, v237, 29
	v_readlane_b32 s19, v237, 30
	v_readlane_b32 s20, v237, 31
	v_readlane_b32 s21, v237, 32
	v_readlane_b32 s22, v237, 33
	v_readlane_b32 s23, v237, 34
	v_add_co_u32_e32 v18, vcc, 0x3000, v22
	global_load_dwordx4 v[2:5], v[12:13], off offset:2048
	global_load_dwordx4 v[6:9], v[10:11], off offset:16
	v_add_co_u32_e64 v10, s[0:1], s5, v14
	v_or_b32_e32 v1, 0x300, v0
	v_readlane_b32 s8, v237, 3
	v_addc_co_u32_e64 v11, s[0:1], 0, v15, s[0:1]
	v_addc_co_u32_e32 v19, vcc, 0, v23, vcc
	v_mad_u64_u32 v[30:31], s[0:1], v1, s4, v[26:27]
	v_lshlrev_b32_e32 v178, 2, v0
	v_readlane_b32 s22, v237, 17
	v_readlane_b32 s23, v237, 18
	v_lshl_add_u64 v[14:15], v[14:15], 0, s[2:3]
	v_add_co_u32_e32 v26, vcc, s5, v30
	v_lshl_add_u64 v[22:23], v[22:23], 0, s[2:3]
	s_nop 0
	v_addc_co_u32_e32 v27, vcc, 0, v31, vcc
	global_load_dword v34, v178, s[22:23] offset:1024
	s_nop 0
	global_load_dwordx4 v[10:13], v[10:11], off offset:2048
	s_nop 0
	global_load_dword v35, v178, s[22:23]
	global_load_dword v36, v178, s[22:23] offset:2048
	v_lshl_add_u64 v[30:31], v[30:31], 0, s[2:3]
	global_load_dwordx4 v[14:17], v[14:15], off offset:16
	v_lshrrev_b32_e32 v171, 6, v0
	global_load_dwordx4 v[18:21], v[18:19], off offset:2048
	v_and_b32_e32 v1, 63, v0
	global_load_dwordx4 v[22:25], v[22:23], off offset:16
	s_nop 0
	global_load_dwordx4 v[26:29], v[26:27], off offset:2048
	s_nop 0
	global_load_dword v37, v178, s[22:23] offset:3072
	v_add_u32_e32 v72, s48, v171
	global_load_dwordx4 v[30:33], v[30:31], off offset:16
	s_movk_i32 s0, 0x4400
	v_mov_b32_e32 v71, 0
	v_cmp_gt_i32_e32 vcc, s0, v72
	v_lshlrev_b32_e32 v176, 4, v1
	v_readlane_b32 s9, v237, 4
	v_readlane_b32 s10, v237, 5
	v_readlane_b32 s11, v237, 6
	v_readlane_b32 s12, v237, 7
	v_readlane_b32 s13, v237, 8
	v_readlane_b32 s14, v237, 9
	v_readlane_b32 s15, v237, 10
	v_readlane_b32 s16, v237, 11
	v_readlane_b32 s17, v237, 12
	v_readlane_b32 s18, v237, 13
	v_readlane_b32 s19, v237, 14
	v_readlane_b32 s20, v237, 15
	v_readlane_b32 s21, v237, 16
	s_waitcnt vmcnt(9)
	v_mul_f32_e32 v2, v2, v34
	v_mul_f32_e32 v4, v4, v34
	v_mul_f32_e32 v3, v3, v34
	v_mul_f32_e32 v5, v5, v34
	v_mul_f32_e32 v6, v6, v34
	s_waitcnt vmcnt(4)
	v_mul_f32_e32 v18, v18, v35
	v_mul_f32_e32 v7, v7, v34
	v_mul_f32_e32 v8, v8, v34
	v_mul_f32_e32 v9, v9, v34
	v_mul_f32_e32 v10, v10, v36
	v_mul_f32_e32 v19, v19, v35
	v_mul_f32_e32 v20, v20, v35
	v_mul_f32_e32 v21, v21, v35
	s_waitcnt vmcnt(3)
	v_mul_f32_e32 v22, v22, v35
	v_mul_f32_e32 v23, v23, v35
	v_mul_f32_e32 v24, v24, v35
	v_mul_f32_e32 v25, v25, v35
	ds_write2st64_b32 v178, v18, v2 offset1:4
	ds_write2st64_b32 v178, v19, v3 offset0:16 offset1:20
	ds_write2st64_b32 v178, v20, v4 offset0:32 offset1:36
	ds_write2st64_b32 v178, v21, v5 offset0:48 offset1:52
	ds_write2st64_b32 v178, v22, v6 offset0:64 offset1:68
	ds_write2st64_b32 v178, v23, v7 offset0:80 offset1:84
	ds_write2st64_b32 v178, v24, v8 offset0:96 offset1:100
	ds_write2st64_b32 v178, v25, v9 offset0:112 offset1:116
	s_waitcnt vmcnt(1)
	v_mul_f32_e32 v4, v26, v37
	v_mul_f32_e32 v11, v11, v36
	ds_write2st64_b32 v178, v10, v4 offset0:8 offset1:12
	v_mul_f32_e32 v4, v27, v37
	v_mul_f32_e32 v12, v12, v36
	ds_write2st64_b32 v178, v11, v4 offset0:24 offset1:28
	v_mul_f32_e32 v4, v28, v37
	v_mul_f32_e32 v13, v13, v36
	ds_write2st64_b32 v178, v12, v4 offset0:40 offset1:44
	v_mul_f32_e32 v4, v29, v37
	v_mul_f32_e32 v14, v14, v36
	ds_write2st64_b32 v178, v13, v4 offset0:56 offset1:60
	s_waitcnt vmcnt(0)
	v_mul_f32_e32 v4, v30, v37
	v_mul_f32_e32 v15, v15, v36
	ds_write2st64_b32 v178, v14, v4 offset0:72 offset1:76
	v_mul_f32_e32 v4, v31, v37
	v_mul_f32_e32 v2, v16, v36
	ds_write2st64_b32 v178, v15, v4 offset0:88 offset1:92
	v_mul_f32_e32 v4, v32, v37
	v_mul_f32_e32 v3, v17, v36
	ds_write2st64_b32 v178, v2, v4 offset0:104 offset1:108
	v_mul_f32_e32 v2, v33, v37
	ds_write2st64_b32 v178, v3, v2 offset0:120 offset1:124
	s_waitcnt lgkmcnt(0)
	s_barrier
	s_and_saveexec_b64 s[0:1], vcc
	s_cbranch_execz .LBB0_61
	v_mbcnt_lo_u32_b32 v2, -1, 0
	v_mbcnt_hi_u32_b32 v2, -1, v2
	v_and_b32_e32 v3, 64, v2
	v_add_u32_e32 v3, 64, v3
	v_xor_b32_e32 v4, 32, v2
	v_cmp_lt_i32_e32 vcc, v4, v3
	s_lshl_b32 s2, s72, 2
	v_ashrrev_i32_e32 v73, 31, v72
	v_cndmask_b32_e32 v4, v2, v4, vcc
	v_lshlrev_b32_e32 v162, 2, v4
	v_xor_b32_e32 v4, 16, v2
	v_cmp_lt_i32_e32 vcc, v4, v3
	v_lshlrev_b32_e32 v66, 2, v1
	v_mov_b64_e32 v[68:69], 0xf280000
	v_cndmask_b32_e32 v4, v2, v4, vcc
	v_lshlrev_b32_e32 v163, 2, v4
	v_xor_b32_e32 v4, 8, v2
	v_cmp_lt_i32_e32 vcc, v4, v3
	s_ashr_i32 s3, s2, 31
	v_cmp_eq_u32_e64 s[4:5], 0, v1
	v_cndmask_b32_e32 v4, v2, v4, vcc
	v_lshlrev_b32_e32 v164, 2, v4
	v_xor_b32_e32 v4, 4, v2
	v_cmp_lt_i32_e32 vcc, v4, v3
	s_lshl_b64 s[6:7], s[2:3], 2
	s_lshl_b64 s[8:9], s[2:3], 5
	v_cndmask_b32_e32 v4, v2, v4, vcc
	v_lshlrev_b32_e32 v165, 2, v4
	v_xor_b32_e32 v4, 2, v2
	v_cmp_lt_i32_e32 vcc, v4, v3
	s_lshl_b64 s[10:11], s[2:3], 11
	s_mov_b64 s[12:13], 0
	v_cndmask_b32_e32 v4, v2, v4, vcc
	v_lshlrev_b32_e32 v166, 2, v4
	v_xor_b32_e32 v4, 1, v2
	v_cmp_lt_i32_e32 vcc, v4, v3
	s_movk_i32 s16, 0x4000
	v_lshlrev_b32_e32 v70, 2, v66
	v_cndmask_b32_e32 v2, v2, v4, vcc
	v_lshlrev_b32_e32 v167, 2, v2
	ds_read_b128 v[138:141], v176
	ds_read_b128 v[2:5], v176 offset:1024
	ds_read_b128 v[6:9], v176 offset:4096
	ds_read_b128 v[142:145], v176 offset:5120
	ds_read_b128 v[146:149], v176 offset:8192
	ds_read_b128 v[10:13], v176 offset:9216
	ds_read_b128 v[14:17], v176 offset:12288
	ds_read_b128 v[150:153], v176 offset:13312
	ds_read_b128 v[154:157], v176 offset:16384
	ds_read_b128 v[18:21], v176 offset:17408
	ds_read_b128 v[22:25], v176 offset:20480
	ds_read_b128 v[158:161], v176 offset:21504
	ds_read_b128 v[172:175], v176 offset:24576
	ds_read_b128 v[26:29], v176 offset:25600
	ds_read_b128 v[30:33], v176 offset:28672
	ds_read_b128 v[180:183], v176 offset:29696
	ds_read_b128 v[34:37], v176 offset:2048
	ds_read_b128 v[128:131], v176 offset:3072
	ds_read_b128 v[184:187], v176 offset:6144
	ds_read_b128 v[38:41], v176 offset:7168
	ds_read_b128 v[42:45], v176 offset:10240
	ds_read_b128 v[116:119], v176 offset:11264
	ds_read_b128 v[188:191], v176 offset:14336
	ds_read_b128 v[46:49], v176 offset:15360
	ds_read_b128 v[50:53], v176 offset:18432
	ds_read_b128 v[104:107], v176 offset:19456
	ds_read_b128 v[192:195], v176 offset:22528
	ds_read_b128 v[54:57], v176 offset:23552
	ds_read_b128 v[58:61], v176 offset:26624
	ds_read_b128 v[92:95], v176 offset:27648
	ds_read_b128 v[196:199], v176 offset:30720
	ds_read_b128 v[62:65], v176 offset:31744
	s_waitcnt lgkmcnt(14)
	v_mov_b32_e32 v132, v2
	v_mov_b32_e32 v133, v143
	v_pk_mov_b32 v[2:3], v[2:3], v[142:143] op_sel:[1,0]
	v_lshlrev_b64 v[142:143], 11, v[72:73]
	v_mov_b32_e32 v74, v37
	s_waitcnt lgkmcnt(13)
	v_mov_b32_e32 v75, v187
	v_mov_b32_e32 v76, v130
	s_waitcnt lgkmcnt(12)
	v_mov_b32_e32 v77, v40
	v_mov_b32_e32 v40, v131
	s_waitcnt lgkmcnt(11)
	v_mov_b32_e32 v78, v45
	s_waitcnt lgkmcnt(9)
	v_mov_b32_e32 v79, v191
	v_mov_b32_e32 v80, v118
	s_waitcnt lgkmcnt(8)
	v_mov_b32_e32 v81, v48
	v_mov_b32_e32 v48, v119
	s_waitcnt lgkmcnt(7)
	v_mov_b32_e32 v82, v53
	s_waitcnt lgkmcnt(5)
	v_mov_b32_e32 v83, v195
	v_mov_b32_e32 v84, v106
	s_waitcnt lgkmcnt(4)
	v_mov_b32_e32 v85, v56
	v_mov_b32_e32 v56, v107
	s_waitcnt lgkmcnt(3)
	v_mov_b32_e32 v86, v61
	s_waitcnt lgkmcnt(1)
	v_mov_b32_e32 v87, v199
	v_mov_b32_e32 v88, v94
	s_waitcnt lgkmcnt(0)
	v_mov_b32_e32 v89, v64
	v_mov_b32_e32 v64, v95
	v_mov_b32_e32 v90, v92
	v_mov_b32_e32 v91, v63
	v_mov_b32_e32 v63, v93
	v_mov_b32_e32 v61, v198
	v_mov_b32_e32 v92, v58
	v_mov_b32_e32 v93, v197
	v_mov_b32_e32 v94, v29
	v_mov_b32_e32 v95, v183
	v_mov_b32_e32 v96, v26
	v_mov_b32_e32 v97, v181
	v_mov_b32_e32 v29, v182
	v_mov_b32_e32 v98, v172
	v_mov_b32_e32 v99, v31
	v_mov_b32_e32 v100, v174
	v_mov_b32_e32 v101, v32
	v_mov_b32_e32 v32, v175
	v_mov_b32_e32 v102, v104
	v_mov_b32_e32 v103, v55
	v_mov_b32_e32 v55, v105
	v_mov_b32_e32 v53, v194
	v_mov_b32_e32 v104, v50
	v_mov_b32_e32 v105, v193
	v_mov_b32_e32 v106, v21
	v_mov_b32_e32 v107, v161
	v_mov_b32_e32 v108, v18
	v_mov_b32_e32 v109, v159
	v_mov_b32_e32 v21, v160
	v_mov_b32_e32 v110, v154
	v_mov_b32_e32 v111, v23
	v_mov_b32_e32 v112, v156
	v_mov_b32_e32 v113, v24
	v_mov_b32_e32 v24, v157
	v_mov_b32_e32 v114, v116
	v_mov_b32_e32 v115, v47
	v_mov_b32_e32 v47, v117
	v_mov_b32_e32 v45, v190
	v_mov_b32_e32 v116, v42
	v_mov_b32_e32 v117, v189
	v_mov_b32_e32 v118, v13
	v_mov_b32_e32 v119, v153
	v_mov_b32_e32 v120, v10
	v_mov_b32_e32 v121, v151
	v_mov_b32_e32 v13, v152
	v_mov_b32_e32 v122, v146
	v_mov_b32_e32 v123, v15
	v_mov_b32_e32 v124, v148
	v_mov_b32_e32 v125, v16
	v_mov_b32_e32 v16, v149
	v_mov_b32_e32 v126, v128
	v_mov_b32_e32 v127, v39
	v_mov_b32_e32 v39, v129
	v_mov_b32_e32 v37, v186
	v_mov_b32_e32 v128, v34
	v_mov_b32_e32 v129, v185
	v_mov_b32_e32 v130, v5
	v_mov_b32_e32 v131, v145
	v_mov_b32_e32 v5, v144
	v_mov_b32_e32 v134, v138
	v_mov_b32_e32 v135, v7
	v_mov_b32_e32 v136, v140
	v_mov_b32_e32 v137, v8
	v_mov_b32_e32 v8, v141
	v_pk_mov_b32 v[6:7], v[138:139], v[6:7] op_sel:[1,0]
	v_pk_mov_b32 v[14:15], v[146:147], v[14:15] op_sel:[1,0]
	v_pk_mov_b32 v[22:23], v[154:155], v[22:23] op_sel:[1,0]
	v_pk_mov_b32 v[30:31], v[172:173], v[30:31] op_sel:[1,0]
	v_pk_mov_b32 v[10:11], v[10:11], v[150:151] op_sel:[1,0]
	v_pk_mov_b32 v[18:19], v[18:19], v[158:159] op_sel:[1,0]
	v_pk_mov_b32 v[26:27], v[26:27], v[180:181] op_sel:[1,0]
	v_pk_mov_b32 v[34:35], v[34:35], v[184:185] op_sel:[1,0]
	v_pk_mov_b32 v[42:43], v[42:43], v[188:189] op_sel:[1,0]
	v_pk_mov_b32 v[50:51], v[50:51], v[192:193] op_sel:[1,0]
	v_pk_mov_b32 v[58:59], v[58:59], v[196:197] op_sel:[1,0]
	v_lshl_add_u64 v[138:139], v[72:73], 2, v[68:69]
	v_lshlrev_b64 v[140:141], 5, v[72:73]
	v_lshl_or_b32 v142, v1, 3, v142
	v_mov_b32_e32 v168, 0x358637bd
	s_mov_b32 s17, 0x800000
	s_movk_i32 s18, 0x43ff
	s_branch .Lp0_pro

.LBB0_61:
	s_or_b64 exec, exec, s[0:1]
	s_bitcmp1_b32 s96, 8
	s_cbranch_scc0 .Lp0_cont
	s_cmp_eq_u32 s99, 1
	s_cbranch_scc1 .Lp0_cont
	s_mov_b32 s99, 1
	v_writelane_b32 v246, s0, 0
	v_writelane_b32 v246, s1, 1
	v_writelane_b32 v246, s2, 2
	v_writelane_b32 v246, s3, 3
	v_writelane_b32 v246, s4, 4
	v_writelane_b32 v246, s5, 5
	v_writelane_b32 v246, s6, 6
	v_writelane_b32 v246, s7, 7
	v_writelane_b32 v246, s8, 8
	v_writelane_b32 v246, s9, 9
	v_writelane_b32 v246, s10, 10
	v_writelane_b32 v246, s11, 11
	v_writelane_b32 v246, s12, 12
	v_writelane_b32 v246, s13, 13
	v_writelane_b32 v246, s14, 14
	v_writelane_b32 v246, s15, 15
	v_writelane_b32 v246, s16, 16
	v_writelane_b32 v246, s17, 17
	v_writelane_b32 v246, s18, 18
	v_writelane_b32 v246, s19, 19
	v_writelane_b32 v246, s20, 20
	v_writelane_b32 v246, s21, 21
	v_writelane_b32 v246, s22, 22
	v_writelane_b32 v246, s23, 23
	v_writelane_b32 v246, s24, 24
	v_writelane_b32 v246, s25, 25
	v_writelane_b32 v246, s26, 26
	v_writelane_b32 v246, s27, 27
	v_writelane_b32 v246, s28, 28
	v_writelane_b32 v246, s29, 29
	v_writelane_b32 v246, s30, 30
	v_writelane_b32 v246, s31, 31
	v_writelane_b32 v246, s32, 32
	v_writelane_b32 v246, s33, 33
	v_writelane_b32 v246, s34, 34
	v_writelane_b32 v246, s35, 35
	v_writelane_b32 v246, s36, 36
	v_writelane_b32 v246, s37, 37
	v_writelane_b32 v246, s38, 38
	v_writelane_b32 v246, s39, 39
	v_writelane_b32 v246, s40, 40
	v_writelane_b32 v246, s41, 41
	v_writelane_b32 v246, s42, 42
	v_writelane_b32 v246, s43, 43
	v_mov_b32_e32 v245, v1
	v_mov_b32_e32 v247, v3
	s_branch .LBB0_16
.Lp0_back:
	v_readlane_b32 s0, v246, 0
	v_readlane_b32 s1, v246, 1
	v_readlane_b32 s2, v246, 2
	v_readlane_b32 s3, v246, 3
	v_readlane_b32 s4, v246, 4
	v_readlane_b32 s5, v246, 5
	v_readlane_b32 s6, v246, 6
	v_readlane_b32 s7, v246, 7
	v_readlane_b32 s8, v246, 8
	v_readlane_b32 s9, v246, 9
	v_readlane_b32 s10, v246, 10
	v_readlane_b32 s11, v246, 11
	v_readlane_b32 s12, v246, 12
	v_readlane_b32 s13, v246, 13
	v_readlane_b32 s14, v246, 14
	v_readlane_b32 s15, v246, 15
	v_readlane_b32 s16, v246, 16
	v_readlane_b32 s17, v246, 17
	v_readlane_b32 s18, v246, 18
	v_readlane_b32 s19, v246, 19
	v_readlane_b32 s20, v246, 20
	v_readlane_b32 s21, v246, 21
	v_readlane_b32 s22, v246, 22
	v_readlane_b32 s23, v246, 23
	v_readlane_b32 s24, v246, 24
	v_readlane_b32 s25, v246, 25
	v_readlane_b32 s26, v246, 26
	v_readlane_b32 s27, v246, 27
	v_readlane_b32 s28, v246, 28
	v_readlane_b32 s29, v246, 29
	v_readlane_b32 s30, v246, 30
	v_readlane_b32 s31, v246, 31
	v_readlane_b32 s32, v246, 32
	v_readlane_b32 s33, v246, 33
	v_readlane_b32 s34, v246, 34
	v_readlane_b32 s35, v246, 35
	v_readlane_b32 s36, v246, 36
	v_readlane_b32 s37, v246, 37
	v_readlane_b32 s38, v246, 38
	v_readlane_b32 s39, v246, 39
	v_readlane_b32 s40, v246, 40
	v_readlane_b32 s41, v246, 41
	v_readlane_b32 s42, v246, 42
	v_readlane_b32 s43, v246, 43
	v_mov_b32_e32 v1, v245
	v_mov_b32_e32 v3, v247
	s_mov_b32 s99, 0
	s_nop 3
.Lp0_cont:
	s_waitcnt vmcnt(0)
	v_mov_b32_e32 v172, 0
	s_waitcnt lgkmcnt(8)
	v_mov_b32_e32 v170, 0
	s_waitcnt lgkmcnt(0)
	s_barrier
	s_mov_b64 s[0:1], exec
	v_readlane_b32 s2, v237, 0
	v_readlane_b32 s3, v237, 1
	s_and_b64 s[2:3], s[0:1], s[2:3]
	s_mov_b64 exec, s[2:3]
	s_cbranch_execz .LBB0_112
	s_add_u32 s2, s54, 0xf33da00
	s_addc_u32 s3, s55, 0
	s_add_u32 s4, s54, 0xf33dc00
	s_addc_u32 s5, s55, 0
	s_add_u32 s6, s54, 0xf33dd00
	s_addc_u32 s7, s55, 0
	s_add_u32 s8, s54, 0xf33de00
	s_addc_u32 s9, s55, 0
	s_add_u32 s10, s54, 0xf33df00
	s_addc_u32 s11, s55, 0
	s_add_u32 s12, s54, 0xf33e000
	s_addc_u32 s13, s55, 0
	s_add_u32 s14, s54, 0xf33e100
	s_addc_u32 s15, s55, 0
	s_add_u32 s16, s54, 0xf33e200
	s_addc_u32 s17, s55, 0
	s_add_u32 s18, s54, 0xf33e300
	s_addc_u32 s19, s55, 0
	s_add_u32 s20, s54, 0xf33e400
	s_addc_u32 s21, s55, 0
	s_add_u32 s22, s54, 0xf33e500
	s_addc_u32 s23, s55, 0
	s_add_u32 s24, s54, 0xf33e600
	s_addc_u32 s25, s55, 0
	s_add_u32 s26, s54, 0xf33e700
	s_addc_u32 s27, s55, 0
	s_add_u32 s28, s54, 0xf33e800
	s_addc_u32 s29, s55, 0
	s_add_u32 s30, s54, 0xf33e900
	s_addc_u32 s31, s55, 0
	s_add_u32 s34, s54, 0xf33ea00
	s_addc_u32 s35, s55, 0
	s_add_u32 s36, s54, 0xf33eb00
	s_addc_u32 s37, s55, 0
	s_mov_b32 s33, 1
	v_mov_b32_e32 v18, 0
	s_waitcnt vmcnt(0) expcnt(0) lgkmcnt(0)
	s_branch .LBB0_64

	.amdhsa_kernel _Z4megaILin1EEv6Params
		.amdhsa_group_segment_fixed_size 81920
		.amdhsa_private_segment_fixed_size 0
		.amdhsa_kernarg_size 456
		.amdhsa_user_sgpr_count 2
		.amdhsa_user_sgpr_dispatch_ptr 0
		.amdhsa_user_sgpr_queue_ptr 0
		.amdhsa_user_sgpr_kernarg_segment_ptr 1
		.amdhsa_user_sgpr_dispatch_id 0
		.amdhsa_user_sgpr_kernarg_preload_length 0
		.amdhsa_user_sgpr_kernarg_preload_offset 0
		.amdhsa_user_sgpr_private_segment_size 0
		.amdhsa_uses_dynamic_stack 0
		.amdhsa_enable_private_segment 0
		.amdhsa_system_sgpr_workgroup_id_x 1
		.amdhsa_system_sgpr_workgroup_id_y 0
		.amdhsa_system_sgpr_workgroup_id_z 0
		.amdhsa_system_sgpr_workgroup_info 0
		.amdhsa_system_vgpr_workitem_id 0
		.amdhsa_next_free_vgpr 248
		.amdhsa_next_free_sgpr 102
		.amdhsa_accum_offset 248
		.amdhsa_reserve_vcc 1
		.amdhsa_float_round_mode_32 0
		.amdhsa_float_round_mode_16_64 0
		.amdhsa_float_denorm_mode_32 3
		.amdhsa_float_denorm_mode_16_64 3
		.amdhsa_dx10_clamp 1
		.amdhsa_ieee_mode 1
		.amdhsa_fp16_overflow 0
		.amdhsa_tg_split 0
		.amdhsa_exception_fp_ieee_invalid_op 0
		.amdhsa_exception_fp_denorm_src 0
		.amdhsa_exception_fp_ieee_div_zero 0
		.amdhsa_exception_fp_ieee_overflow 0
		.amdhsa_exception_fp_ieee_underflow 0
		.amdhsa_exception_fp_ieee_inexact 0
		.amdhsa_exception_int_div_zero 0
	.end_amdhsa_kernel

amdhsa.kernels:
  - .agpr_count:     0
    .args:
      - .offset:         0
        .size:           200
        .value_kind:     by_value
      - .offset:         200
        .size:           4
        .value_kind:     hidden_block_count_x
      - .offset:         204
        .size:           4
        .value_kind:     hidden_block_count_y
      - .offset:         208
        .size:           4
        .value_kind:     hidden_block_count_z
      - .offset:         212
        .size:           2
        .value_kind:     hidden_group_size_x
      - .offset:         214
        .size:           2
        .value_kind:     hidden_group_size_y
      - .offset:         216
        .size:           2
        .value_kind:     hidden_group_size_z
      - .offset:         218
        .size:           2
        .value_kind:     hidden_remainder_x
      - .offset:         220
        .size:           2
        .value_kind:     hidden_remainder_y
      - .offset:         222
        .size:           2
        .value_kind:     hidden_remainder_z
      - .offset:         240
        .size:           8
        .value_kind:     hidden_global_offset_x
      - .offset:         248
        .size:           8
        .value_kind:     hidden_global_offset_y
      - .offset:         256
        .size:           8
        .value_kind:     hidden_global_offset_z
      - .offset:         264
        .size:           2
        .value_kind:     hidden_grid_dims
    .group_segment_fixed_size: 81920
    .kernarg_segment_align: 8
    .kernarg_segment_size: 456
    .language:       OpenCL C
    .language_version:
      - 2
      - 0
    .max_flat_workgroup_size: 256
    .name:           _Z4megaILin1EEv6Params
    .private_segment_fixed_size: 0
    .sgpr_count:     108
    .sgpr_spill_count: 277
    .symbol:         _Z4megaILin1EEv6Params.kd
    .uniform_work_group_size: 1
    .uses_dynamic_stack: false
    .vgpr_count:     248
    .vgpr_spill_count: 0
    .wavefront_size: 64
